# nt hint on the read-once conv-row loads of the gdn prep phase
# speedup vs baseline: 1.0228x; 1.0228x over previous
; #define GDN_LOAD_ROWS(it) do { const int n_ = (it) & 31, h_ = ((it) >> 5) & 7, b_ = (it) >> 8, col_ = a_sec * 1024 + h_ * 128 + a_c4; \
;         _Pragma("unroll") for (int r = 0; r < 16; ++r) { const int rr = a_r0 + r - 3, tr = n_ * 64 + rr; \
;             xv[r] = (a_rg < 5 && rr < 64 && tr >= 0) ? *(const u32x2*)(P0 + (size_t)(b_ * 2048 + tr) * LDP0 + col_) : (u32x2){0u, 0u}; } } while (0)
; DI void phase_gdn_prep(const Params& p, unsigned char* smem) {
;     ...
;     const int a_rg = tid / 96, a_cq = tid - a_rg * 96, a_sec = a_cq >> 5, a_c4 = (a_cq & 31) * 4, a_r0 = a_rg * 13;
;     u32x2 xv[16];
;     ...
;     if ((int)blockIdx.x < 2048) GDN_LOAD_ROWS((int)blockIdx.x);
.LBB0_211:
	s_or_b64 exec, exec, s[0:1]
	s_mov_b32 s0, 0x2aaaaaab
	v_mul_hi_i32 v2, v46, s0
	v_lshrrev_b32_e32 v3, 31, v2
	v_ashrrev_i32_e32 v2, 4, v2
	s_cmpk_lt_i32 s2, 0x800
	v_add_u32_e32 v8, v2, v3
	s_movk_i32 s0, 0xffa0
	s_cselect_b64 s[4:5], -1, 0
	v_mad_u64_u32 v[2:3], s[0:1], v8, s0, v[46:47]
	v_lshlrev_b32_e32 v4, 2, v46
	v_ashrrev_i32_e32 v3, 5, v2
	v_and_b32_e32 v9, 0x7c, v4
	v_mul_lo_u32 v47, v8, 13
	s_and_b64 vcc, exec, s[4:5]
	s_cbranch_vccz .LBB0_245
	s_lshl_b32 s0, s2, 2
	s_lshl_b32 s1, s2, 6
	s_and_b32 s0, s0, 0x380
	s_and_b32 s6, s1, 0x7c0
	v_lshlrev_b32_e32 v4, 10, v3
	v_or3_b32 v4, v4, s0, v9
	s_movk_i32 s0, 0x1e0
	v_add3_u32 v6, s6, -3, v47
	v_mov_b32_e32 v48, 0
	v_cmp_gt_i32_e32 vcc, s0, v46
	v_ashrrev_i32_e32 v5, 31, v4
	v_cmp_lt_i32_e64 s[0:1], -1, v6
	v_mov_b32_e32 v49, v48
	s_and_b32 s3, s83, 0xfffff800
	v_lshl_add_u64 v[4:5], v[4:5], 1, s[86:87]
	s_and_b64 s[8:9], vcc, s[0:1]
	v_mov_b64_e32 v[50:51], v[48:49]
	s_and_saveexec_b64 s[0:1], s[8:9]
	s_cbranch_execz .LBB0_214
	v_add_u32_e32 v6, s3, v6
	s_movk_i32 s7, 0x2200
	v_mad_i64_i32 v[6:7], s[8:9], v6, s7, v[4:5]
	global_load_dwordx2 v[50:51], v[6:7], off nt
.LBB0_214:
	s_or_b64 exec, exec, s[0:1]
	v_add3_u32 v6, s6, -2, v47
	v_cmp_lt_i32_e64 s[0:1], -1, v6
	s_and_b64 s[8:9], vcc, s[0:1]
	s_and_saveexec_b64 s[0:1], s[8:9]
	s_cbranch_execz .LBB0_216
	v_add_u32_e32 v6, s3, v6
	s_movk_i32 s7, 0x2200
	v_mad_i64_i32 v[6:7], s[8:9], v6, s7, v[4:5]
	global_load_dwordx2 v[48:49], v[6:7], off nt
.LBB0_216:
	s_or_b64 exec, exec, s[0:1]
	v_add3_u32 v6, s6, -1, v47
	v_mov_b32_e32 v54, 0
	v_cmp_lt_i32_e64 s[0:1], -1, v6
	v_mov_b32_e32 v55, v54
	s_and_b64 s[8:9], vcc, s[0:1]
	v_mov_b64_e32 v[52:53], v[54:55]
	s_and_saveexec_b64 s[0:1], s[8:9]
	s_cbranch_execz .LBB0_218
	v_add_u32_e32 v6, s3, v6
	s_movk_i32 s7, 0x2200
	v_mad_i64_i32 v[6:7], s[8:9], v6, s7, v[4:5]
	global_load_dwordx2 v[52:53], v[6:7], off nt
.LBB0_218:
	s_or_b64 exec, exec, s[0:1]
	v_add_u32_e32 v6, s6, v47
	v_cmp_lt_i32_e64 s[0:1], -1, v6
	s_and_b64 s[8:9], vcc, s[0:1]
	s_and_saveexec_b64 s[0:1], s[8:9]
	s_cbranch_execz .LBB0_220
	v_add_u32_e32 v6, s3, v6
	s_movk_i32 s7, 0x2200
	v_mad_i64_i32 v[6:7], s[8:9], v6, s7, v[4:5]
	global_load_dwordx2 v[54:55], v[6:7], off nt
.LBB0_220:
	s_or_b64 exec, exec, s[0:1]
	s_or_b32 s0, s6, 1
	v_add_u32_e32 v6, s0, v47
	v_mov_b32_e32 v58, 0
	v_cmp_lt_i32_e64 s[0:1], -1, v6
	v_mov_b32_e32 v59, v58
	s_and_b64 s[8:9], vcc, s[0:1]
	v_mov_b64_e32 v[56:57], v[58:59]
	s_and_saveexec_b64 s[0:1], s[8:9]
	s_cbranch_execz .LBB0_222
	v_add_u32_e32 v6, s3, v6
	s_movk_i32 s7, 0x2200
	v_mad_i64_i32 v[6:7], s[8:9], v6, s7, v[4:5]
	global_load_dwordx2 v[56:57], v[6:7], off nt
.LBB0_222:
	s_or_b64 exec, exec, s[0:1]
	s_or_b32 s0, s6, 2
	v_add_u32_e32 v6, s0, v47
	v_cmp_lt_i32_e64 s[0:1], -1, v6
	s_and_b64 s[8:9], vcc, s[0:1]
	s_and_saveexec_b64 s[0:1], s[8:9]
	s_cbranch_execz .LBB0_224
	v_add_u32_e32 v6, s3, v6
	s_movk_i32 s7, 0x2200
	v_mad_i64_i32 v[6:7], s[8:9], v6, s7, v[4:5]
	global_load_dwordx2 v[58:59], v[6:7], off nt
.LBB0_224:
	s_or_b64 exec, exec, s[0:1]
	s_or_b32 s0, s6, 3
	v_add_u32_e32 v6, s0, v47
	v_mov_b32_e32 v62, 0
	v_cmp_lt_i32_e64 s[0:1], -1, v6
	v_mov_b32_e32 v63, v62
	s_and_b64 s[8:9], vcc, s[0:1]
	v_mov_b64_e32 v[60:61], v[62:63]
	s_and_saveexec_b64 s[0:1], s[8:9]
	s_cbranch_execz .LBB0_226
	v_add_u32_e32 v6, s3, v6
	s_movk_i32 s7, 0x2200
	v_mad_i64_i32 v[6:7], s[8:9], v6, s7, v[4:5]
	global_load_dwordx2 v[60:61], v[6:7], off nt
; #define GDN_LOAD_ROWS(it) do { const int n_ = (it) & 31, h_ = ((it) >> 5) & 7, b_ = (it) >> 8, col_ = a_sec * 1024 + h_ * 128 + a_c4; \
;         _Pragma("unroll") for (int r = 0; r < 16; ++r) { const int rr = a_r0 + r - 3, tr = n_ * 64 + rr; \
;             xv[r] = (a_rg < 5 && rr < 64 && tr >= 0) ? *(const u32x2*)(P0 + (size_t)(b_ * 2048 + tr) * LDP0 + col_) : (u32x2){0u, 0u}; } } while (0)
; DI void phase_gdn_prep(const Params& p, unsigned char* smem) {
;     ...
;     if ((int)blockIdx.x < 2048) GDN_LOAD_ROWS((int)blockIdx.x);
.LBB0_226:
	s_or_b64 exec, exec, s[0:1]
	s_or_b32 s0, s6, 4
	v_add_u32_e32 v6, s0, v47
	v_cmp_lt_i32_e64 s[0:1], -1, v6
	s_and_b64 s[8:9], vcc, s[0:1]
	s_and_saveexec_b64 s[0:1], s[8:9]
	s_cbranch_execz .LBB0_228
	v_add_u32_e32 v6, s3, v6
	s_movk_i32 s7, 0x2200
	v_mad_i64_i32 v[6:7], s[8:9], v6, s7, v[4:5]
	global_load_dwordx2 v[62:63], v[6:7], off nt
.LBB0_228:
	s_or_b64 exec, exec, s[0:1]
	s_or_b32 s0, s6, 5
	v_add_u32_e32 v6, s0, v47
	v_mov_b32_e32 v66, 0
	v_cmp_lt_i32_e64 s[0:1], -1, v6
	v_mov_b32_e32 v67, v66
	s_and_b64 s[8:9], vcc, s[0:1]
	v_mov_b64_e32 v[64:65], v[66:67]
	s_and_saveexec_b64 s[0:1], s[8:9]
	s_cbranch_execz .LBB0_230
	v_add_u32_e32 v6, s3, v6
	s_movk_i32 s7, 0x2200
	v_mad_i64_i32 v[6:7], s[8:9], v6, s7, v[4:5]
	global_load_dwordx2 v[64:65], v[6:7], off nt
.LBB0_230:
	s_or_b64 exec, exec, s[0:1]
	s_or_b32 s0, s6, 6
	v_add_u32_e32 v6, s0, v47
	v_cmp_lt_i32_e64 s[0:1], -1, v6
	s_and_b64 s[8:9], vcc, s[0:1]
	s_and_saveexec_b64 s[0:1], s[8:9]
	s_cbranch_execz .LBB0_232
	v_add_u32_e32 v6, s3, v6
	s_movk_i32 s7, 0x2200
	v_mad_i64_i32 v[6:7], s[8:9], v6, s7, v[4:5]
	global_load_dwordx2 v[66:67], v[6:7], off nt
.LBB0_232:
	s_or_b64 exec, exec, s[0:1]
	s_or_b32 s0, s6, 7
	v_add_u32_e32 v6, s0, v47
	v_mov_b32_e32 v70, 0
	v_cmp_lt_i32_e64 s[0:1], -1, v6
	v_mov_b32_e32 v71, v70
	s_and_b64 s[8:9], vcc, s[0:1]
	v_mov_b64_e32 v[68:69], v[70:71]
	s_and_saveexec_b64 s[0:1], s[8:9]
	s_cbranch_execz .LBB0_234
	v_add_u32_e32 v6, s3, v6
	s_movk_i32 s7, 0x2200
	v_mad_i64_i32 v[6:7], s[8:9], v6, s7, v[4:5]
	global_load_dwordx2 v[68:69], v[6:7], off nt
.LBB0_234:
	s_or_b64 exec, exec, s[0:1]
	s_or_b32 s0, s6, 8
	v_add_u32_e32 v6, s0, v47
	v_cmp_lt_i32_e64 s[0:1], -1, v6
	s_and_b64 s[8:9], vcc, s[0:1]
	s_and_saveexec_b64 s[0:1], s[8:9]
	s_cbranch_execz .LBB0_236
	v_add_u32_e32 v6, s3, v6
	s_movk_i32 s7, 0x2200
	v_mad_i64_i32 v[6:7], s[8:9], v6, s7, v[4:5]
	global_load_dwordx2 v[70:71], v[6:7], off nt
.LBB0_236:
	s_or_b64 exec, exec, s[0:1]
	s_or_b32 s0, s6, 9
	v_add_u32_e32 v6, s0, v47
	v_mov_b32_e32 v76, 0
	v_cmp_lt_i32_e64 s[0:1], -1, v6
	v_mov_b32_e32 v77, v76
	s_and_b64 s[8:9], vcc, s[0:1]
	v_mov_b64_e32 v[74:75], v[76:77]
	s_and_saveexec_b64 s[0:1], s[8:9]
	s_cbranch_execz .LBB0_238
	v_add_u32_e32 v6, s3, v6
	s_movk_i32 s7, 0x2200
	v_mad_i64_i32 v[6:7], s[8:9], v6, s7, v[4:5]
	global_load_dwordx2 v[74:75], v[6:7], off nt
.LBB0_238:
	s_or_b64 exec, exec, s[0:1]
	s_or_b32 s0, s6, 10
	v_add_u32_e32 v6, s0, v47
	v_cmp_lt_i32_e64 s[0:1], -1, v6
	s_and_b64 s[8:9], vcc, s[0:1]
	s_and_saveexec_b64 s[0:1], s[8:9]
	s_cbranch_execz .LBB0_240
	v_add_u32_e32 v6, s3, v6
	s_movk_i32 s7, 0x2200
	v_mad_i64_i32 v[6:7], s[8:9], v6, s7, v[4:5]
	global_load_dwordx2 v[76:77], v[6:7], off nt
.LBB0_240:
	s_or_b64 exec, exec, s[0:1]
	s_or_b32 s0, s6, 11
	v_add_u32_e32 v10, s0, v47
	v_mov_b32_e32 v6, 0
	v_cmp_lt_i32_e64 s[0:1], -1, v10
	v_mov_b32_e32 v7, v6
	s_and_b64 s[8:9], vcc, s[0:1]
	v_mov_b64_e32 v[78:79], v[6:7]
	s_and_saveexec_b64 s[0:1], s[8:9]
	s_cbranch_execz .LBB0_242
	v_add_u32_e32 v7, s3, v10
	s_movk_i32 s7, 0x2200
	v_mad_i64_i32 v[10:11], s[8:9], v7, s7, v[4:5]
	global_load_dwordx2 v[78:79], v[10:11], off nt
.LBB0_242:
	s_or_b64 exec, exec, s[0:1]
	s_or_b32 s0, s6, 12
	v_add_u32_e32 v7, s0, v47
	s_movk_i32 s0, 0x180
	v_cmp_gt_i32_e32 vcc, s0, v46
	v_cmp_lt_i32_e64 s[0:1], -1, v7
	s_and_b64 s[6:7], vcc, s[0:1]
	v_mov_b32_e32 v80, 0
	s_and_saveexec_b64 s[0:1], s[6:7]
	s_cbranch_execz .LBB0_244
	v_add_u32_e32 v6, s3, v7
	s_movk_i32 s3, 0x2200
	v_mad_i64_i32 v[4:5], s[6:7], v6, s3, v[4:5]
	global_load_dwordx2 v[80:81], v[4:5], off nt
	s_waitcnt vmcnt(0)
	v_mov_b32_e32 v6, v81

; #define GDN_LOAD_ROWS(it) do { const int n_ = (it) & 31, h_ = ((it) >> 5) & 7, b_ = (it) >> 8, col_ = a_sec * 1024 + h_ * 128 + a_c4; \
;         _Pragma("unroll") for (int r = 0; r < 16; ++r) { const int rr = a_r0 + r - 3, tr = n_ * 64 + rr; \
;             xv[r] = (a_rg < 5 && rr < 64 && tr >= 0) ? *(const u32x2*)(P0 + (size_t)(b_ * 2048 + tr) * LDP0 + col_) : (u32x2){0u, 0u}; } } while (0)
; DI void phase_gdn_prep(const Params& p, unsigned char* smem) {
;     ...
;     if ((int)blockIdx.x < 2048) GDN_LOAD_ROWS((int)blockIdx.x);
;     ...
;         if (item + (int)gridDim.x < 2048) GDN_LOAD_ROWS(item + (int)gridDim.x);
.LBB0_411:
	s_or_b64 exec, exec, s[28:29]
	s_add_i32 s49, s49, s94
	s_cmpk_gt_i32 s49, 0x7ff
	s_cselect_b64 s[28:29], -1, 0
	s_and_b64 vcc, exec, s[28:29]
	s_cbranch_vccnz .LBB0_445
	s_lshl_b32 s12, s49, 2
	s_and_b32 s12, s12, 0x380
	v_or_b32_e32 v2, s12, v83
	s_lshl_b32 s12, s49, 6
	s_and_b32 s13, s12, 0x7c0
	v_add_u32_e32 v4, s13, v84
	s_lshl_b32 s12, s49, 3
	v_ashrrev_i32_e32 v3, 31, v2
	v_cmp_lt_i32_e32 vcc, -1, v4
	v_mov_b32_e32 v48, v36
	v_mov_b32_e32 v49, v36
	s_and_b32 s12, s12, 0xfffff800
	v_lshl_add_u64 v[2:3], v[2:3], 1, s[86:87]
	s_and_b64 s[34:35], s[4:5], vcc
	v_mov_b64_e32 v[50:51], v[48:49]
	s_and_saveexec_b64 s[30:31], s[34:35]
	s_cbranch_execz .LBB0_414
	v_add_u32_e32 v6, s12, v4
	v_mad_i64_i32 v[6:7], s[34:35], v6, s37, v[2:3]
	global_load_dwordx2 v[50:51], v[6:7], off nt
.LBB0_414:
	s_or_b64 exec, exec, s[30:31]
	v_add_u32_e32 v6, 1, v4
	v_cmp_lt_i32_e32 vcc, -1, v6
	s_and_b64 s[34:35], s[4:5], vcc
	s_and_saveexec_b64 s[30:31], s[34:35]
	s_cbranch_execz .LBB0_416
	v_add_u32_e32 v6, s12, v6
	v_mad_i64_i32 v[6:7], s[34:35], v6, s37, v[2:3]
	global_load_dwordx2 v[48:49], v[6:7], off nt
.LBB0_416:
	s_or_b64 exec, exec, s[30:31]
	v_add_u32_e32 v6, 2, v4
	v_cmp_lt_i32_e32 vcc, -1, v6
	v_mov_b32_e32 v37, v36
	s_and_b64 s[34:35], s[4:5], vcc
	v_mov_b64_e32 v[52:53], v[36:37]
	s_and_saveexec_b64 s[30:31], s[34:35]
	s_cbranch_execz .LBB0_418
	v_add_u32_e32 v6, s12, v6
	v_mad_i64_i32 v[6:7], s[34:35], v6, s37, v[2:3]
	global_load_dwordx2 v[52:53], v[6:7], off nt
.LBB0_418:
	s_or_b64 exec, exec, s[30:31]
	v_add_u32_e32 v6, s13, v47
	v_cmp_lt_i32_e32 vcc, -1, v6
	s_and_b64 s[34:35], s[4:5], vcc
	v_mov_b64_e32 v[54:55], v[36:37]
	s_and_saveexec_b64 s[30:31], s[34:35]
	s_cbranch_execz .LBB0_420
	v_add_u32_e32 v6, s12, v6
	v_mad_i64_i32 v[6:7], s[34:35], v6, s37, v[2:3]
	global_load_dwordx2 v[54:55], v[6:7], off nt
.LBB0_420:
	s_or_b64 exec, exec, s[30:31]
	v_add_u32_e32 v6, 4, v4
	v_cmp_lt_i32_e32 vcc, -1, v6
	v_mov_b32_e32 v37, v36
	s_and_b64 s[34:35], s[4:5], vcc
	v_mov_b64_e32 v[56:57], v[36:37]
	s_and_saveexec_b64 s[30:31], s[34:35]
	s_cbranch_execz .LBB0_422
	v_add_u32_e32 v6, s12, v6
	v_mad_i64_i32 v[6:7], s[34:35], v6, s37, v[2:3]
	global_load_dwordx2 v[56:57], v[6:7], off nt
.LBB0_422:
	s_or_b64 exec, exec, s[30:31]
	v_add_u32_e32 v6, 5, v4
	v_cmp_lt_i32_e32 vcc, -1, v6
	s_and_b64 s[34:35], s[4:5], vcc
	v_mov_b64_e32 v[58:59], v[36:37]
	s_and_saveexec_b64 s[30:31], s[34:35]
	s_cbranch_execz .LBB0_424
	v_add_u32_e32 v6, s12, v6
	v_mad_i64_i32 v[6:7], s[34:35], v6, s37, v[2:3]
	global_load_dwordx2 v[58:59], v[6:7], off nt
.LBB0_424:
	s_or_b64 exec, exec, s[30:31]
	v_add_u32_e32 v6, 6, v4
	v_cmp_lt_i32_e32 vcc, -1, v6
	v_mov_b32_e32 v37, v36
	s_and_b64 s[34:35], s[4:5], vcc
	v_mov_b64_e32 v[60:61], v[36:37]
	s_and_saveexec_b64 s[30:31], s[34:35]
	s_cbranch_execz .LBB0_426
	v_add_u32_e32 v6, s12, v6
	v_mad_i64_i32 v[6:7], s[34:35], v6, s37, v[2:3]
	global_load_dwordx2 v[60:61], v[6:7], off nt
.LBB0_426:
	s_or_b64 exec, exec, s[30:31]
	v_add_u32_e32 v6, 7, v4
	v_cmp_lt_i32_e32 vcc, -1, v6
	s_and_b64 s[34:35], s[4:5], vcc
	v_mov_b64_e32 v[62:63], v[36:37]
	s_and_saveexec_b64 s[30:31], s[34:35]
	s_cbranch_execz .LBB0_428
	v_add_u32_e32 v6, s12, v6
	v_mad_i64_i32 v[6:7], s[34:35], v6, s37, v[2:3]
	global_load_dwordx2 v[62:63], v[6:7], off nt
.LBB0_428:
	s_or_b64 exec, exec, s[30:31]
	v_add_u32_e32 v6, 8, v4
	v_cmp_lt_i32_e32 vcc, -1, v6
	v_mov_b32_e32 v37, v36
	s_and_b64 s[34:35], s[4:5], vcc
	v_mov_b64_e32 v[64:65], v[36:37]
	s_and_saveexec_b64 s[30:31], s[34:35]
	s_cbranch_execz .LBB0_430
	v_add_u32_e32 v6, s12, v6
	v_mad_i64_i32 v[6:7], s[34:35], v6, s37, v[2:3]
	global_load_dwordx2 v[64:65], v[6:7], off nt
.LBB0_430:
	s_or_b64 exec, exec, s[30:31]
	v_add_u32_e32 v6, 9, v4
	v_cmp_lt_i32_e32 vcc, -1, v6
	s_and_b64 s[34:35], s[4:5], vcc
	v_mov_b64_e32 v[66:67], v[36:37]
	s_and_saveexec_b64 s[30:31], s[34:35]
	s_cbranch_execz .LBB0_432
	v_add_u32_e32 v6, s12, v6
	v_mad_i64_i32 v[6:7], s[34:35], v6, s37, v[2:3]
	global_load_dwordx2 v[66:67], v[6:7], off nt
.LBB0_432:
	s_or_b64 exec, exec, s[30:31]
	v_add_u32_e32 v6, 10, v4
	v_cmp_lt_i32_e32 vcc, -1, v6
	v_mov_b32_e32 v37, v36
	s_and_b64 s[34:35], s[4:5], vcc
	v_mov_b64_e32 v[68:69], v[36:37]
	s_and_saveexec_b64 s[30:31], s[34:35]
	s_cbranch_execz .LBB0_434
	v_add_u32_e32 v6, s12, v6
	v_mad_i64_i32 v[6:7], s[34:35], v6, s37, v[2:3]
	global_load_dwordx2 v[68:69], v[6:7], off nt
.LBB0_434:
	s_or_b64 exec, exec, s[30:31]
	v_add_u32_e32 v6, 11, v4
	v_cmp_lt_i32_e32 vcc, -1, v6
	s_and_b64 s[34:35], s[4:5], vcc
	v_mov_b64_e32 v[70:71], v[36:37]
	s_and_saveexec_b64 s[30:31], s[34:35]
	s_cbranch_execz .LBB0_436
	v_add_u32_e32 v6, s12, v6
	v_mad_i64_i32 v[6:7], s[34:35], v6, s37, v[2:3]
	global_load_dwordx2 v[70:71], v[6:7], off nt
.LBB0_436:
	s_or_b64 exec, exec, s[30:31]
	v_add_u32_e32 v6, 12, v4
	v_cmp_lt_i32_e32 vcc, -1, v6
	v_mov_b32_e32 v37, v36
	s_and_b64 s[34:35], s[4:5], vcc
	v_mov_b64_e32 v[74:75], v[36:37]
	s_and_saveexec_b64 s[30:31], s[34:35]
	s_cbranch_execz .LBB0_438
	v_add_u32_e32 v6, s12, v6
	v_mad_i64_i32 v[6:7], s[34:35], v6, s37, v[2:3]
	global_load_dwordx2 v[74:75], v[6:7], off nt
.LBB0_438:
	s_or_b64 exec, exec, s[30:31]
	v_add_u32_e32 v6, 13, v4
	v_cmp_lt_i32_e32 vcc, -1, v6
	s_and_b64 s[34:35], s[4:5], vcc
	v_mov_b64_e32 v[76:77], v[36:37]
	s_and_saveexec_b64 s[30:31], s[34:35]
	s_cbranch_execz .LBB0_440
	v_add_u32_e32 v6, s12, v6
	v_mad_i64_i32 v[6:7], s[34:35], v6, s37, v[2:3]
	global_load_dwordx2 v[76:77], v[6:7], off nt
.LBB0_440:
	s_or_b64 exec, exec, s[30:31]
	v_add_u32_e32 v6, 14, v4
	v_cmp_lt_i32_e32 vcc, -1, v6
	v_mov_b32_e32 v37, v36
	s_and_b64 s[34:35], s[4:5], vcc
	v_mov_b64_e32 v[78:79], v[36:37]
	s_and_saveexec_b64 s[30:31], s[34:35]
	s_cbranch_execz .LBB0_442
	v_add_u32_e32 v6, s12, v6
	v_mad_i64_i32 v[6:7], s[34:35], v6, s37, v[2:3]
	global_load_dwordx2 v[78:79], v[6:7], off nt
.LBB0_442:
	s_or_b64 exec, exec, s[30:31]
	v_add_u32_e32 v4, 15, v4
	v_cmp_lt_i32_e32 vcc, -1, v4
	s_and_b64 s[34:35], s[6:7], vcc
	v_mov_b32_e32 v81, 0
	v_mov_b32_e32 v80, 0
	s_and_saveexec_b64 s[30:31], s[34:35]
	s_cbranch_execz .LBB0_444
	v_add_u32_e32 v4, s12, v4
	v_mad_i64_i32 v[2:3], s[12:13], v4, s37, v[2:3]
	global_load_dwordx2 v[80:81], v[2:3], off nt
